# c15 + row-sum chains as v_pk_add_f32 (15 pk + 1 add instead of 32 adds) in MLA and DIFF loops
# baseline (speedup 1.0000x reference)
.LBB0_871:
	s_add_i32 s80, s75, -3
	s_lshl_b32 s76, s74, 14
	s_add_i32 s8, s69, s76
	v_lshl_add_u64 v[2:3], v[226:227], 0, s[34:35]
	s_mov_b32 m0, s8
	s_nop 0
	global_load_lds_dwordx4 v[2:3], off
	s_add_i32 m0, s8, 0x2000
	s_mul_i32 s8, s60, 0x6300
	s_add_i32 s61, s68, s8
	global_load_lds_dwordx4 v[226:227], off
	s_add_i32 m0, s61, 0xc000
	s_add_i32 s8, s75, -1
	s_cmp_lt_u32 s8, s77
	s_cselect_b32 s8, s8, s73
	s_lshl_b32 s8, s8, 6
	s_lshl_b64 s[58:59], s[8:9], 12
	v_lshl_add_u64 v[2:3], v[218:219], 0, s[58:59]
	global_load_lds_dwordx4 v[2:3], off
	v_lshl_add_u64 v[2:3], v[2:3], 0, s[12:13]
	s_add_i32 m0, s61, 0xe100
	s_lshl_b64 s[82:83], s[8:9], 7
	global_load_lds_dwordx4 v[2:3], off
	v_lshl_add_u64 v[2:3], v[224:225], 0, s[82:83]
	s_add_i32 m0, s61, 0x10200
	s_nop 0
	global_load_lds_dwordx4 v[2:3], off
	s_mul_i32 s8, s79, 0x6300
	s_add_i32 s8, s8, 0
	v_add_u32_e32 v0, s8, v237
	ds_read_b128 v[2:5], v0 offset:49152
	ds_read_b128 v[6:9], v0 offset:50176
	s_waitcnt lgkmcnt(0)
	v_mfma_f32_32x32x16_bf16 v[112:127], v[2:5], v[188:191], 0
	v_mfma_f32_32x32x16_bf16 v[128:143], v[6:9], v[188:191], 0
	ds_read_b128 v[2:5], v0 offset:51264
	ds_read_b128 v[6:9], v0 offset:52288
	s_waitcnt lgkmcnt(0)
	v_mfma_f32_32x32x16_bf16 v[112:127], v[2:5], v[184:187], v[112:127]
	v_mfma_f32_32x32x16_bf16 v[128:143], v[6:9], v[184:187], v[128:143]
	ds_read_b128 v[2:5], v0 offset:53376
	ds_read_b128 v[6:9], v0 offset:54400
	s_waitcnt lgkmcnt(0)
	v_mfma_f32_32x32x16_bf16 v[112:127], v[2:5], v[180:183], v[112:127]
	v_mfma_f32_32x32x16_bf16 v[128:143], v[6:9], v[180:183], v[128:143]
	ds_read_b128 v[2:5], v0 offset:55488
	ds_read_b128 v[6:9], v0 offset:56512
	s_waitcnt lgkmcnt(0)
	v_mfma_f32_32x32x16_bf16 v[112:127], v[2:5], v[176:179], v[112:127]
	v_mfma_f32_32x32x16_bf16 v[128:143], v[6:9], v[176:179], v[128:143]
	ds_read_b128 v[2:5], v0 offset:57600
	ds_read_b128 v[6:9], v0 offset:58624
	s_waitcnt lgkmcnt(0)
	v_mfma_f32_32x32x16_bf16 v[112:127], v[2:5], v[172:175], v[112:127]
	v_mfma_f32_32x32x16_bf16 v[128:143], v[6:9], v[172:175], v[128:143]
	ds_read_b128 v[2:5], v0 offset:59712
	ds_read_b128 v[6:9], v0 offset:60736
	s_waitcnt lgkmcnt(0)
	v_mfma_f32_32x32x16_bf16 v[112:127], v[2:5], v[168:171], v[112:127]
	v_mfma_f32_32x32x16_bf16 v[128:143], v[6:9], v[168:171], v[128:143]
	ds_read_b128 v[2:5], v0 offset:61824
	ds_read_b128 v[6:9], v0 offset:62848
	s_waitcnt lgkmcnt(0)
	v_mfma_f32_32x32x16_bf16 v[112:127], v[2:5], v[164:167], v[112:127]
	v_mfma_f32_32x32x16_bf16 v[128:143], v[6:9], v[164:167], v[128:143]
	ds_read_b128 v[2:5], v0 offset:63936
	ds_read_b128 v[6:9], v0 offset:64960
	v_add_u32_e32 v0, 0xc000, v0
	s_waitcnt lgkmcnt(0)
	v_mfma_f32_32x32x16_bf16 v[112:127], v[2:5], v[160:163], v[112:127]
	ds_read_b128 v[2:5], v0 offset:17920
	ds_read_b128 v[10:13], v0 offset:16896
	v_mfma_f32_32x32x16_bf16 v[128:143], v[6:9], v[160:163], v[128:143]
	ds_read_b128 v[6:9], v0 offset:20032
	ds_read_b128 v[192:195], v0 offset:19008
	ds_read_b128 v[196:199], v0 offset:22144
	ds_read_b128 v[200:203], v0 offset:21120
	ds_read_b128 v[204:207], v0 offset:24256
	ds_read_b128 v[208:211], v0 offset:23232
	v_pk_add_f32 v[246:247], v[96:97], v[98:99]
	v_pk_add_f32 v[246:247], v[100:101], v[246:247]
	s_waitcnt lgkmcnt(0)
	v_mfma_f32_32x32x16_bf16 v[112:127], v[10:13], v[156:159], v[112:127]
	v_pk_add_f32 v[246:247], v[102:103], v[246:247]
	v_pk_add_f32 v[246:247], v[104:105], v[246:247]
	v_pk_add_f32 v[246:247], v[106:107], v[246:247]
	v_mfma_f32_32x32x16_bf16 v[128:143], v[2:5], v[156:159], v[128:143]
	v_pk_add_f32 v[246:247], v[108:109], v[246:247]
	v_pk_add_f32 v[246:247], v[110:111], v[246:247]
	v_pk_add_f32 v[246:247], v[80:81], v[246:247]
	v_pk_add_f32 v[246:247], v[82:83], v[246:247]
	v_mfma_f32_32x32x16_bf16 v[112:127], v[192:195], v[152:155], v[112:127]
	v_pk_add_f32 v[246:247], v[84:85], v[246:247]
	v_pk_add_f32 v[246:247], v[86:87], v[246:247]
	v_pk_add_f32 v[246:247], v[88:89], v[246:247]
	v_mfma_f32_32x32x16_bf16 v[128:143], v[6:9], v[152:155], v[128:143]
	v_pk_add_f32 v[246:247], v[90:91], v[246:247]
	v_pk_add_f32 v[246:247], v[92:93], v[246:247]
	v_pk_add_f32 v[246:247], v[94:95], v[246:247]
	v_add_f32_e32 v14, v246, v247
	v_mov_b32_e32 v15, v14
	s_nop 1
	v_permlane32_swap_b32_e32 v14, v15
	v_mfma_f32_32x32x16_bf16 v[112:127], v[200:203], v[148:151], v[112:127]
	v_cvt_pk_bf16_f32 v192, v96, v97
	v_cvt_pk_bf16_f32 v193, v98, v99
	v_cvt_pk_bf16_f32 v194, v100, v101
	v_cvt_pk_bf16_f32 v195, v102, v103
	v_cvt_pk_bf16_f32 v10, v104, v105
	v_cvt_pk_bf16_f32 v11, v106, v107
	v_cvt_pk_bf16_f32 v12, v108, v109
	v_mfma_f32_32x32x16_bf16 v[128:143], v[196:199], v[148:151], v[128:143]
	v_cvt_pk_bf16_f32 v13, v110, v111
	v_cvt_pk_bf16_f32 v6, v80, v81
	v_cvt_pk_bf16_f32 v7, v82, v83
	v_cvt_pk_bf16_f32 v8, v84, v85
	v_cvt_pk_bf16_f32 v9, v86, v87
	v_cvt_pk_bf16_f32 v2, v88, v89
	v_cvt_pk_bf16_f32 v3, v90, v91
	v_mfma_f32_32x32x16_bf16 v[112:127], v[208:211], v[144:147], v[112:127]
	v_cvt_pk_bf16_f32 v4, v92, v93
	v_cvt_pk_bf16_f32 v5, v94, v95
	v_mfma_f32_32x32x16_bf16 v[128:143], v[204:207], v[144:147], v[128:143]
	s_cmp_gt_i32 s80, s72
	s_cbranch_scc1 .Lold_mla_odd
	v_lshl_add_u32 v0, s60, 14, v235
	ds_read_b64_tr_b16 v[208:209], v0 offset:0
	ds_read_b64_tr_b16 v[210:211], v0 offset:0x800
	ds_read_b64_tr_b16 v[204:205], v0 offset:0x1000
	ds_read_b64_tr_b16 v[206:207], v0 offset:0x1800
	ds_read_b64_tr_b16 v[200:201], v0 offset:0x2000
	ds_read_b64_tr_b16 v[202:203], v0 offset:0x2800
	ds_read_b64_tr_b16 v[196:197], v0 offset:0x3000
	ds_read_b64_tr_b16 v[198:199], v0 offset:0x3800
	s_nop 1
	v_max3_f32 v245, v112, v113, v114
	v_max3_f32 v246, v128, v129, v130
	v_max3_f32 v245, v245, v115, v116
	v_max3_f32 v246, v246, v131, v132
	v_max3_f32 v245, v245, v117, v118
	v_max3_f32 v246, v246, v133, v134
	v_max3_f32 v245, v245, v119, v120
	v_max3_f32 v246, v246, v135, v136
	v_max3_f32 v245, v245, v121, v122
	v_max3_f32 v246, v246, v137, v138
	v_max3_f32 v245, v245, v123, v124
	v_max3_f32 v246, v246, v139, v140
	v_max3_f32 v245, v245, v125, v126
	v_max3_f32 v246, v246, v141, v142
	v_max_f32_e32 v245, v245, v127
	v_max_f32_e32 v246, v246, v143
	v_max_f32_e32 v245, v245, v246
	v_mov_b32_e32 v246, v245
	s_nop 1
	v_permlane32_swap_b32_e32 v245, v246
	v_max_f32_e32 v245, v245, v246
	v_sub_f32_e32 v246, v245, v236
	v_cmp_ge_f32_e32 vcc, s29, v246
	s_cmp_eq_u64 vcc, exec
	v_mov_b32_e32 v240, 1.0
	s_cbranch_scc0 .Lfm_odd_ev

.LBB0_876:
	s_waitcnt vmcnt(0)
	s_add_i32 s60, s74, 1
	s_cmp_lg_u32 s74, 2
	s_cselect_b32 s81, s60, 0
	s_waitcnt vmcnt(0)
	s_barrier
	s_lshl_b32 s78, s81, 14
	s_add_i32 s60, s69, s78
	v_lshl_add_u64 v[2:3], v[222:223], 0, s[58:59]
	v_lshl_add_u64 v[4:5], v[2:3], 0, s[14:15]
	s_mov_b32 m0, s60
	s_add_i32 s8, s8, s70
	global_load_lds_dwordx4 v[4:5], off
	v_lshl_add_u64 v[2:3], v[2:3], 0, s[16:17]
	s_add_i32 m0, s60, 0x2000
	s_add_i32 s82, s8, s71
	global_load_lds_dwordx4 v[2:3], off
	s_add_i32 m0, s82, 0xc000
	s_cmp_ge_u32 s75, s77
	s_cselect_b64 s[58:59], -1, 0
	s_cmp_lt_u32 s75, s77
	s_cselect_b32 s8, s75, s73
	s_lshl_b32 s8, s8, 6
	s_lshl_b64 s[60:61], s[8:9], 12
	v_lshl_add_u64 v[2:3], v[218:219], 0, s[60:61]
	global_load_lds_dwordx4 v[2:3], off
	v_lshl_add_u64 v[2:3], v[2:3], 0, s[12:13]
	s_add_i32 m0, s82, 0xe100
	s_lshl_b64 s[60:61], s[8:9], 7
	global_load_lds_dwordx4 v[2:3], off
	v_lshl_add_u64 v[2:3], v[224:225], 0, s[60:61]
	s_add_i32 m0, s82, 0x10200
	s_nop 0
	global_load_lds_dwordx4 v[2:3], off
	s_mul_i32 s8, s74, 0x6300
	v_add_u32_e32 v0, s8, v238
	ds_read_b128 v[2:5], v0 offset:49152
	ds_read_b128 v[6:9], v0 offset:50176
	s_waitcnt lgkmcnt(0)
	v_mfma_f32_32x32x16_bf16 v[112:127], v[2:5], v[188:191], 0
	v_mfma_f32_32x32x16_bf16 v[128:143], v[6:9], v[188:191], 0
	ds_read_b128 v[2:5], v0 offset:51264
	ds_read_b128 v[6:9], v0 offset:52288
	s_waitcnt lgkmcnt(0)
	v_mfma_f32_32x32x16_bf16 v[112:127], v[2:5], v[184:187], v[112:127]
	v_mfma_f32_32x32x16_bf16 v[128:143], v[6:9], v[184:187], v[128:143]
	ds_read_b128 v[2:5], v0 offset:53376
	ds_read_b128 v[6:9], v0 offset:54400
	s_waitcnt lgkmcnt(0)
	v_mfma_f32_32x32x16_bf16 v[112:127], v[2:5], v[180:183], v[112:127]
	v_mfma_f32_32x32x16_bf16 v[128:143], v[6:9], v[180:183], v[128:143]
	ds_read_b128 v[2:5], v0 offset:55488
	ds_read_b128 v[6:9], v0 offset:56512
	s_waitcnt lgkmcnt(0)
	v_mfma_f32_32x32x16_bf16 v[112:127], v[2:5], v[176:179], v[112:127]
	v_mfma_f32_32x32x16_bf16 v[128:143], v[6:9], v[176:179], v[128:143]
	ds_read_b128 v[2:5], v0 offset:57600
	ds_read_b128 v[6:9], v0 offset:58624
	s_waitcnt lgkmcnt(0)
	v_mfma_f32_32x32x16_bf16 v[112:127], v[2:5], v[172:175], v[112:127]
	v_mfma_f32_32x32x16_bf16 v[128:143], v[6:9], v[172:175], v[128:143]
	ds_read_b128 v[2:5], v0 offset:59712
	ds_read_b128 v[6:9], v0 offset:60736
	s_waitcnt lgkmcnt(0)
	v_mfma_f32_32x32x16_bf16 v[112:127], v[2:5], v[168:171], v[112:127]
	v_mfma_f32_32x32x16_bf16 v[128:143], v[6:9], v[168:171], v[128:143]
	ds_read_b128 v[2:5], v0 offset:61824
	ds_read_b128 v[6:9], v0 offset:62848
	s_waitcnt lgkmcnt(0)
	v_mfma_f32_32x32x16_bf16 v[112:127], v[2:5], v[164:167], v[112:127]
	v_mfma_f32_32x32x16_bf16 v[128:143], v[6:9], v[164:167], v[128:143]
	ds_read_b128 v[2:5], v0 offset:63936
	ds_read_b128 v[6:9], v0 offset:64960
	v_add_u32_e32 v0, 0xc000, v0
	s_waitcnt lgkmcnt(0)
	v_mfma_f32_32x32x16_bf16 v[112:127], v[2:5], v[160:163], v[112:127]
	ds_read_b128 v[2:5], v0 offset:17920
	ds_read_b128 v[10:13], v0 offset:16896
	v_mfma_f32_32x32x16_bf16 v[128:143], v[6:9], v[160:163], v[128:143]
	ds_read_b128 v[6:9], v0 offset:20032
	ds_read_b128 v[192:195], v0 offset:19008
	ds_read_b128 v[196:199], v0 offset:22144
	ds_read_b128 v[200:203], v0 offset:21120
	ds_read_b128 v[204:207], v0 offset:24256
	ds_read_b128 v[208:211], v0 offset:23232
	v_pk_add_f32 v[246:247], v[96:97], v[98:99]
	v_pk_add_f32 v[246:247], v[100:101], v[246:247]
	s_waitcnt lgkmcnt(0)
	v_mfma_f32_32x32x16_bf16 v[112:127], v[10:13], v[156:159], v[112:127]
	v_pk_add_f32 v[246:247], v[102:103], v[246:247]
	v_pk_add_f32 v[246:247], v[104:105], v[246:247]
	v_pk_add_f32 v[246:247], v[106:107], v[246:247]
	v_mfma_f32_32x32x16_bf16 v[128:143], v[2:5], v[156:159], v[128:143]
	v_pk_add_f32 v[246:247], v[108:109], v[246:247]
	v_pk_add_f32 v[246:247], v[110:111], v[246:247]
	v_pk_add_f32 v[246:247], v[80:81], v[246:247]
	v_pk_add_f32 v[246:247], v[82:83], v[246:247]
	v_mfma_f32_32x32x16_bf16 v[112:127], v[192:195], v[152:155], v[112:127]
	v_pk_add_f32 v[246:247], v[84:85], v[246:247]
	v_pk_add_f32 v[246:247], v[86:87], v[246:247]
	v_pk_add_f32 v[246:247], v[88:89], v[246:247]
	v_mfma_f32_32x32x16_bf16 v[128:143], v[6:9], v[152:155], v[128:143]
	v_pk_add_f32 v[246:247], v[90:91], v[246:247]
	v_pk_add_f32 v[246:247], v[92:93], v[246:247]
	v_pk_add_f32 v[246:247], v[94:95], v[246:247]
	v_add_f32_e32 v241, v246, v247
	v_mov_b32_e32 v242, v241
	s_nop 1
	v_permlane32_swap_b32_e32 v241, v242
	v_mfma_f32_32x32x16_bf16 v[112:127], v[200:203], v[148:151], v[112:127]
	v_cvt_pk_bf16_f32 v192, v96, v97
	v_cvt_pk_bf16_f32 v193, v98, v99
	v_cvt_pk_bf16_f32 v194, v100, v101
	v_cvt_pk_bf16_f32 v195, v102, v103
	v_cvt_pk_bf16_f32 v10, v104, v105
	v_cvt_pk_bf16_f32 v11, v106, v107
	v_cvt_pk_bf16_f32 v12, v108, v109
	v_mfma_f32_32x32x16_bf16 v[128:143], v[196:199], v[148:151], v[128:143]
	v_cvt_pk_bf16_f32 v13, v110, v111
	v_cvt_pk_bf16_f32 v6, v80, v81
	v_cvt_pk_bf16_f32 v7, v82, v83
	v_cvt_pk_bf16_f32 v8, v84, v85
	v_cvt_pk_bf16_f32 v9, v86, v87
	v_cvt_pk_bf16_f32 v2, v88, v89
	v_cvt_pk_bf16_f32 v3, v90, v91
	v_mfma_f32_32x32x16_bf16 v[112:127], v[208:211], v[144:147], v[112:127]
	v_cvt_pk_bf16_f32 v4, v92, v93
	v_cvt_pk_bf16_f32 v5, v94, v95
	v_mfma_f32_32x32x16_bf16 v[128:143], v[204:207], v[144:147], v[128:143]
	s_cmp_lt_i32 s80, s72
	s_cbranch_scc0 .Lold_mla_even
	v_lshl_add_u32 v243, s79, 14, v235
	ds_read_b64_tr_b16 v[208:209], v243 offset:0
	ds_read_b64_tr_b16 v[210:211], v243 offset:0x800
	ds_read_b64_tr_b16 v[204:205], v243 offset:0x1000
	ds_read_b64_tr_b16 v[206:207], v243 offset:0x1800
	ds_read_b64_tr_b16 v[200:201], v243 offset:0x2000
	ds_read_b64_tr_b16 v[202:203], v243 offset:0x2800
	ds_read_b64_tr_b16 v[196:197], v243 offset:0x3000
	ds_read_b64_tr_b16 v[198:199], v243 offset:0x3800
	s_nop 1
	v_max3_f32 v245, v112, v113, v114
	v_max3_f32 v246, v128, v129, v130
	v_max3_f32 v245, v245, v115, v116
	v_max3_f32 v246, v246, v131, v132
	v_max3_f32 v245, v245, v117, v118
	v_max3_f32 v246, v246, v133, v134
	v_max3_f32 v245, v245, v119, v120
	v_max3_f32 v246, v246, v135, v136
	v_max3_f32 v245, v245, v121, v122
	v_max3_f32 v246, v246, v137, v138
	v_max3_f32 v245, v245, v123, v124
	v_max3_f32 v246, v246, v139, v140
	v_max3_f32 v245, v245, v125, v126
	v_max3_f32 v246, v246, v141, v142
	v_max_f32_e32 v245, v245, v127
	v_max_f32_e32 v246, v246, v143
	v_max_f32_e32 v245, v245, v246
	v_mov_b32_e32 v246, v245
	s_nop 1
	v_permlane32_swap_b32_e32 v245, v246
	v_max_f32_e32 v245, v245, v246
	v_sub_f32_e32 v246, v245, v236
	v_cmp_ge_f32_e32 vcc, s29, v246
	s_cmp_eq_u64 vcc, exec
	v_mov_b32_e32 v0, 1.0
	s_cbranch_scc0 .Lfm_even_ev

.LBB0_1422:
	s_lshl_b32 s18, s44, 14
	s_add_i32 s52, s81, s18
	s_mov_b32 m0, s52
	v_lshl_add_u64 v[0:1], v[194:195], 0, s[14:15]
	global_load_lds_dwordx4 v[194:195], off
	s_add_i32 m0, s52, 0x2000
	s_mul_i32 s52, s54, 0x2100
	s_add_i32 s52, s22, s52
	global_load_lds_dwordx4 v[0:1], off
	s_add_i32 m0, s52, 0xc000
	s_add_i32 s52, s45, -1
	s_cmp_lt_u32 s52, s2
	s_cselect_b32 s55, s52, s3
	s_lshl_b32 s56, s55, 6
	v_mad_u64_u32 v[0:1], s[52:53], s56, v209, v[192:193]
	v_lshl_add_u64 v[0:1], v[0:1], 0, s[10:11]
	global_load_lds_dwordx4 v[0:1], off
	s_mul_i32 s52, s55, 0x60000
	s_mul_hi_u32 s53, s56, 0x1800
	s_mul_i32 s55, s69, 0x2100
	s_add_i32 s71, s55, 0
	s_sub_i32 s55, s65, 64
	v_cvt_f32_u32_e32 v0, s55
	v_add_u32_e32 v166, s71, v220
	v_add_u32_e32 v167, s71, v217
	ds_read_b128 v[4:7], v166 offset:49152
	ds_read_b128 v[8:11], v167 offset:49152
	v_sub_f32_e32 v196, v0, v161
	v_fma_f32 v0, v210, v196, -v221
	v_cvt_pk_bf16_f32 v1, v0, v3
	v_lshlrev_b32_e32 v1, 16, v1
	v_sub_f32_e32 v0, v0, v1
	v_cvt_pk_bf16_f32 v2, v0, v3
	v_lshlrev_b32_e32 v2, 16, v2
	v_sub_f32_e32 v0, v0, v2
	v_cvt_pk_bf16_f32 v1, v1, v2
	v_cvt_pk_bf16_f32 v0, v0, v3
	s_nop 0
	v_cndmask_b32_e64 v2, 0, v0, s[4:5]
	v_cndmask_b32_e64 v0, 0, v160, s[4:5]
	v_cndmask_b32_e64 v1, 0, v1, s[4:5]
	s_nop 1
	v_mfma_f32_32x32x16_bf16 v[128:143], v[248:251], v[0:3], 0
	v_mfma_f32_32x32x16_bf16 v[112:127], v[252:255], v[0:3], 0
	v_pk_add_f32 v[246:247], v[96:97], v[98:99]
	v_pk_add_f32 v[246:247], v[100:101], v[246:247]
	s_waitcnt lgkmcnt(0)
	v_mfma_f32_32x32x16_bf16 v[128:143], v[8:11], v[156:159], v[128:143]
	v_pk_add_f32 v[246:247], v[102:103], v[246:247]
	v_pk_add_f32 v[246:247], v[104:105], v[246:247]
	v_pk_add_f32 v[246:247], v[106:107], v[246:247]
	v_pk_add_f32 v[246:247], v[108:109], v[246:247]
	v_mfma_f32_32x32x16_bf16 v[112:127], v[4:7], v[156:159], v[112:127]
	ds_read_b128 v[4:7], v166 offset:51264
	ds_read_b128 v[8:11], v167 offset:51264
	v_pk_add_f32 v[246:247], v[110:111], v[246:247]
	v_pk_add_f32 v[246:247], v[80:81], v[246:247]
	v_pk_add_f32 v[246:247], v[82:83], v[246:247]
	s_waitcnt lgkmcnt(0)
	v_mfma_f32_32x32x16_bf16 v[128:143], v[8:11], v[152:155], v[128:143]
	v_pk_add_f32 v[246:247], v[84:85], v[246:247]
	v_pk_add_f32 v[246:247], v[86:87], v[246:247]
	v_pk_add_f32 v[246:247], v[88:89], v[246:247]
	v_mfma_f32_32x32x16_bf16 v[112:127], v[4:7], v[152:155], v[112:127]
	ds_read_b128 v[4:7], v166 offset:53376
	ds_read_b128 v[8:11], v167 offset:53376
	v_pk_add_f32 v[246:247], v[90:91], v[246:247]
	v_pk_add_f32 v[246:247], v[92:93], v[246:247]
	v_pk_add_f32 v[246:247], v[94:95], v[246:247]
	v_add_f32_e32 v223, v246, v247
	v_mov_b32_e32 v224, v223
	s_waitcnt lgkmcnt(0)
	v_mfma_f32_32x32x16_bf16 v[128:143], v[8:11], v[148:151], v[128:143]
	v_permlane32_swap_b32_e32 v223, v224
	v_mfma_f32_32x32x16_bf16 v[112:127], v[4:7], v[148:151], v[112:127]
	ds_read_b128 v[4:7], v166 offset:55488
	ds_read_b128 v[8:11], v167 offset:55488
	v_cvt_pk_bf16_f32 v166, v96, v97
	v_cvt_pk_bf16_f32 v167, v98, v99
	v_cvt_pk_bf16_f32 v168, v100, v101
	v_cvt_pk_bf16_f32 v169, v102, v103
	v_cvt_pk_bf16_f32 v12, v104, v105
	v_cvt_pk_bf16_f32 v13, v106, v107
	s_waitcnt lgkmcnt(0)
	v_mfma_f32_32x32x16_bf16 v[128:143], v[8:11], v[144:147], v[128:143]
	v_cvt_pk_bf16_f32 v14, v108, v109
	v_cvt_pk_bf16_f32 v15, v110, v111
	v_cvt_pk_bf16_f32 v8, v80, v81
	v_cvt_pk_bf16_f32 v9, v82, v83
	v_cvt_pk_bf16_f32 v10, v84, v85
	v_cvt_pk_bf16_f32 v11, v86, v87
	v_mfma_f32_32x32x16_bf16 v[112:127], v[4:7], v[144:147], v[112:127]
	v_cvt_pk_bf16_f32 v4, v88, v89
	v_cvt_pk_bf16_f32 v5, v90, v91
	v_cvt_pk_bf16_f32 v6, v92, v93
	v_cvt_pk_bf16_f32 v7, v94, v95
	v_lshl_add_u32 v1, s54, 14, v215
	ds_read_b64_tr_b16 v[182:183], v1 offset:0
	ds_read_b64_tr_b16 v[184:185], v1 offset:0x800
	ds_read_b64_tr_b16 v[178:179], v1 offset:0x1000
	ds_read_b64_tr_b16 v[180:181], v1 offset:0x1800
	s_add_i32 s70, s45, -3
	s_add_i32 s54, s19, s45
	ds_read_b64_tr_b16 v[174:175], v1 offset:0x2000
	s_cmp_eq_u32 s54, 3
	ds_read_b64_tr_b16 v[176:177], v1 offset:0x2800
	s_cselect_b64 s[54:55], -1, 0
	ds_read_b64_tr_b16 v[170:171], v1 offset:0x3000
	v_cndmask_b32_e64 v2, 0, 1, s[54:55]
	ds_read_b64_tr_b16 v[172:173], v1 offset:0x3800
	s_cmp_lt_i32 s70, s31
	s_cbranch_scc0 .Lold_odd
	v_max3_f32 v245, v128, v129, v130
	v_max3_f32 v246, v112, v113, v114
	v_max3_f32 v245, v245, v131, v132
	v_max3_f32 v246, v246, v115, v116
	v_max3_f32 v245, v245, v133, v134
	v_max3_f32 v246, v246, v117, v118
	v_max3_f32 v245, v245, v135, v136
	v_max3_f32 v246, v246, v119, v120
	v_max3_f32 v245, v245, v137, v138
	v_max3_f32 v246, v246, v121, v122
	v_max3_f32 v245, v245, v139, v140
	v_max3_f32 v246, v246, v123, v124
	v_max3_f32 v245, v245, v141, v142
	v_max3_f32 v246, v246, v125, v126
	v_max_f32_e32 v245, v245, v143
	v_max_f32_e32 v246, v246, v127
	v_max_f32_e32 v245, v245, v246
	v_mov_b32_e32 v246, v245
	s_nop 1
	v_permlane32_swap_b32_e32 v245, v246
	v_max_f32_e32 v245, v245, v246
	v_cmp_ge_f32_e32 vcc, s68, v245
	s_cmp_eq_u64 vcc, exec
	v_mov_b32_e32 v225, 1.0
	s_cbranch_scc0 .Lf_odd_resc

.LBB0_1437:
	s_waitcnt vmcnt(0)
	s_add_i32 s54, s44, 1
	s_cmp_lg_u32 s44, 2
	s_cselect_b32 s67, s54, 0
	s_waitcnt vmcnt(0)
	s_barrier
	s_lshl_b32 s66, s67, 14
	s_add_i32 s54, s81, s66
	v_lshl_add_u64 v[4:5], v[190:191], 0, s[52:53]
	s_mov_b32 m0, s54
	s_add_i32 s52, s71, s82
	global_load_lds_dwordx4 v[4:5], off
	v_lshl_add_u64 v[4:5], v[4:5], 0, s[14:15]
	s_add_i32 m0, s54, 0x2000
	s_add_i32 s52, s52, s27
	global_load_lds_dwordx4 v[4:5], off
	s_add_i32 m0, s52, 0xc000
	s_cmp_ge_u32 s45, s2
	s_cselect_b64 s[52:53], -1, 0
	s_cmp_lt_u32 s45, s2
	s_cselect_b32 s54, s45, s3
	s_lshl_b32 s54, s54, 6
	v_mad_u64_u32 v[4:5], s[54:55], s54, v209, v[192:193]
	v_lshl_add_u64 v[4:5], v[4:5], 0, s[10:11]
	global_load_lds_dwordx4 v[4:5], off
	v_cvt_f32_u32_e32 v1, s65
	s_mul_i32 s54, s44, 0x2100
	s_add_i32 s54, s54, 0
	v_add_u32_e32 v166, s54, v220
	v_sub_f32_e32 v196, v1, v161
	v_add_u32_e32 v167, s54, v217
	v_fma_f32 v1, v210, v196, -v221
	ds_read_b128 v[4:7], v166 offset:49152
	ds_read_b128 v[8:11], v167 offset:49152
	v_cvt_pk_bf16_f32 v2, v1, v3
	v_lshlrev_b32_e32 v2, 16, v2
	v_sub_f32_e32 v1, v1, v2
	v_cvt_pk_bf16_f32 v12, v1, v3
	v_lshlrev_b32_e32 v12, 16, v12
	v_sub_f32_e32 v1, v1, v12
	v_cvt_pk_bf16_f32 v12, v2, v12
	v_cvt_pk_bf16_f32 v1, v1, v3
	s_nop 0
	v_cndmask_b32_e64 v2, 0, v1, s[4:5]
	v_cndmask_b32_e64 v1, 0, v12, s[4:5]
	s_nop 1
	v_mfma_f32_32x32x16_bf16 v[128:143], v[248:251], v[0:3], 0
	s_nop 0
	v_mfma_f32_32x32x16_bf16 v[112:127], v[252:255], v[0:3], 0
	v_pk_add_f32 v[246:247], v[96:97], v[98:99]
	v_pk_add_f32 v[246:247], v[100:101], v[246:247]
	s_waitcnt lgkmcnt(0)
	v_mfma_f32_32x32x16_bf16 v[128:143], v[8:11], v[156:159], v[128:143]
	v_pk_add_f32 v[246:247], v[102:103], v[246:247]
	v_pk_add_f32 v[246:247], v[104:105], v[246:247]
	v_pk_add_f32 v[246:247], v[106:107], v[246:247]
	v_pk_add_f32 v[246:247], v[108:109], v[246:247]
	v_mfma_f32_32x32x16_bf16 v[112:127], v[4:7], v[156:159], v[112:127]
	ds_read_b128 v[4:7], v166 offset:51264
	ds_read_b128 v[8:11], v167 offset:51264
	v_pk_add_f32 v[246:247], v[110:111], v[246:247]
	v_pk_add_f32 v[246:247], v[80:81], v[246:247]
	v_pk_add_f32 v[246:247], v[82:83], v[246:247]
	s_waitcnt lgkmcnt(0)
	v_mfma_f32_32x32x16_bf16 v[128:143], v[8:11], v[152:155], v[128:143]
	v_pk_add_f32 v[246:247], v[84:85], v[246:247]
	v_pk_add_f32 v[246:247], v[86:87], v[246:247]
	v_pk_add_f32 v[246:247], v[88:89], v[246:247]
	v_mfma_f32_32x32x16_bf16 v[112:127], v[4:7], v[152:155], v[112:127]
	ds_read_b128 v[4:7], v166 offset:53376
	ds_read_b128 v[8:11], v167 offset:53376
	v_pk_add_f32 v[246:247], v[90:91], v[246:247]
	v_pk_add_f32 v[246:247], v[92:93], v[246:247]
	v_pk_add_f32 v[246:247], v[94:95], v[246:247]
	v_add_f32_e32 v1, v246, v247
	v_mov_b32_e32 v2, v1
	s_waitcnt lgkmcnt(0)
	v_mfma_f32_32x32x16_bf16 v[128:143], v[8:11], v[148:151], v[128:143]
	v_permlane32_swap_b32_e32 v1, v2
	v_mfma_f32_32x32x16_bf16 v[112:127], v[4:7], v[148:151], v[112:127]
	ds_read_b128 v[4:7], v166 offset:55488
	ds_read_b128 v[8:11], v167 offset:55488
	v_cvt_pk_bf16_f32 v166, v96, v97
	v_cvt_pk_bf16_f32 v167, v98, v99
	v_cvt_pk_bf16_f32 v168, v100, v101
	v_cvt_pk_bf16_f32 v169, v102, v103
	v_cvt_pk_bf16_f32 v12, v104, v105
	v_cvt_pk_bf16_f32 v13, v106, v107
	s_waitcnt lgkmcnt(0)
	v_mfma_f32_32x32x16_bf16 v[128:143], v[8:11], v[144:147], v[128:143]
	v_cvt_pk_bf16_f32 v14, v108, v109
	v_cvt_pk_bf16_f32 v15, v110, v111
	v_cvt_pk_bf16_f32 v8, v80, v81
	v_cvt_pk_bf16_f32 v9, v82, v83
	v_cvt_pk_bf16_f32 v10, v84, v85
	v_cvt_pk_bf16_f32 v11, v86, v87
	v_mfma_f32_32x32x16_bf16 v[112:127], v[4:7], v[144:147], v[112:127]
	v_cvt_pk_bf16_f32 v4, v88, v89
	v_cvt_pk_bf16_f32 v5, v90, v91
	v_cvt_pk_bf16_f32 v6, v92, v93
	v_cvt_pk_bf16_f32 v7, v94, v95
	v_lshl_add_u32 v162, s69, 14, v215
	ds_read_b64_tr_b16 v[182:183], v162 offset:0
	ds_read_b64_tr_b16 v[184:185], v162 offset:0x800
	ds_read_b64_tr_b16 v[178:179], v162 offset:0x1000
	ds_read_b64_tr_b16 v[180:181], v162 offset:0x1800
	s_add_i32 s54, s64, s45
	ds_read_b64_tr_b16 v[174:175], v162 offset:0x2000
	s_cmp_eq_u32 s54, 4
	ds_read_b64_tr_b16 v[176:177], v162 offset:0x2800
	s_cselect_b64 s[54:55], -1, 0
	ds_read_b64_tr_b16 v[170:171], v162 offset:0x3000
	v_cndmask_b32_e64 v80, 0, 1, s[54:55]
	ds_read_b64_tr_b16 v[172:173], v162 offset:0x3800
	s_add_i32 s98, s70, 2
	s_cmp_le_i32 s98, s31
	s_cbranch_scc0 .Lold_even
	v_max3_f32 v245, v128, v129, v130
	v_max3_f32 v246, v112, v113, v114
	v_max3_f32 v245, v245, v131, v132
	v_max3_f32 v246, v246, v115, v116
	v_max3_f32 v245, v245, v133, v134
	v_max3_f32 v246, v246, v117, v118
	v_max3_f32 v245, v245, v135, v136
	v_max3_f32 v246, v246, v119, v120
	v_max3_f32 v245, v245, v137, v138
	v_max3_f32 v246, v246, v121, v122
	v_max3_f32 v245, v245, v139, v140
	v_max3_f32 v246, v246, v123, v124
	v_max3_f32 v245, v245, v141, v142
	v_max3_f32 v246, v246, v125, v126
	v_max_f32_e32 v245, v245, v143
	v_max_f32_e32 v246, v246, v127
	v_max_f32_e32 v245, v245, v246
	v_mov_b32_e32 v246, v245
	s_nop 1
	v_permlane32_swap_b32_e32 v245, v246
	v_max_f32_e32 v245, v245, v246
	v_cmp_ge_f32_e32 vcc, s68, v245
	s_cmp_eq_u64 vcc, exec
	v_mov_b32_e32 v196, 1.0
	s_cbranch_scc0 .Lf_even_resc
